# v15 + redundant s_waitcnt lgkmcnt(0) after the pre-MFMA barrier removed in the GEMM K-loop (the same wait already precedes the barrier)
# baseline (speedup 1.0000x reference)
; #define PG8_STAGE(bufoff, gbase, voff) do { _Pragma("unroll") for (int _i = 0; _i < 2; ++_i) \
;         __builtin_amdgcn_global_load_lds((const unsigned*)((const char*)(gbase) + (voff)[_i]), (PG8_LAS unsigned*)(lds + (bufoff) + ldsw + _i * 8192), 16, 0, 0); } while (0)
; #define PG8_LDA(dst, b, h) do { _Pragma("unroll") for (int m = 0; m < 4; ++m) _Pragma("unroll") for (int k = 0; k < 2; ++k) dst[m][k] = *(const PG8_LAS bf16x8*)(lds + PG8_SA(b, h) + aoff + m * 2048 + k * 1024); } while (0)
; template <class Epi, class Sched, bool ALIGN_EPI = false, bool SP2 = false>
; __device__ __forceinline__ void gemm_phase(PG8_LAS unsigned char* lds, const Gemm g, const Sched& S, const Epi& E) {
;     ...
;     for (;;) {
;         const bool has_next = S.next(ui + 1, nxt);
;         const char* nA = has_next ? (const char*)g.A + (size_t)nxt.pm * tstep : cA; const char* nB = has_next ? (const char*)g.Bt + (size_t)nxt.pn * tstep : cB;
;         for (int t = 0; t < nt; t += 2) {
;             const bool last = (t == nt - 2);
;             const char* a1 = cA + (size_t)(t + 1) * kstep;
;             const char* a2 = last ? nA : cA + (size_t)(t + 2) * kstep; const char* b2 = last ? nB : cB + (size_t)(t + 2) * kstep;
;             const char* a3 = a2 + kstep; const char* b3 = b2 + kstep;
;             if (last && has_next) S.a_ready(nxt);
;             if constexpr (SP2) {
;             PG8_LDB(B0, 0, 0); PG8_LDB(B1, 0, 1); PG8_SCHED; PG8_LDA(At, 0, 0); PG8_STAGE(PG8_SA(1, 1), a1 + hstep, voffA);
;             PG8_WAIT_V(8); PG8_WAIT_L(0); PG8_BAR; PG8_MMA(0, 0, At, B0); PG8_MMA(0, 1, At, B1); PG8_BAR; PG8_SCHED;
;             PG8_LDA(At, 0, 1); PG8_STAGE(PG8_SB(0, 0), b2, voffB); PG8_STAGE(PG8_SB(0, 1), b2 + hstep, voffB); PG8_STAGE(PG8_SA(0, 0), a2, voffA);
;             PG8_WAIT_V(8); PG8_WAIT_L(0); PG8_BAR; PG8_MMA(1, 0, At, B0); PG8_MMA(1, 1, At, B1); PG8_BAR; PG8_SCHED;
;             PG8_LDB(B0, 1, 0); PG8_LDB(B1, 1, 1); PG8_SCHED; PG8_LDA(At, 1, 0); PG8_STAGE(PG8_SA(0, 1), a2 + hstep, voffA);
;             PG8_WAIT_V(8); PG8_WAIT_L(0); PG8_BAR; PG8_MMA(0, 0, At, B0); PG8_MMA(0, 1, At, B1); PG8_BAR; PG8_SCHED;
;             PG8_LDA(At, 1, 1); PG8_STAGE(PG8_SB(1, 0), b3, voffB); PG8_STAGE(PG8_SB(1, 1), b3 + hstep, voffB); PG8_STAGE(PG8_SA(1, 0), a3, voffA);
;             PG8_WAIT_V(8); PG8_WAIT_L(0); PG8_BAR; PG8_MMA(1, 0, At, B0); PG8_MMA(1, 1, At, B1); PG8_BAR; PG8_SCHED;
.LBB0_307:
	s_add_i32 s26, s8, 2
	s_add_u32 s27, s2, 0x80
	s_addc_u32 s9, s3, 0
	s_add_i32 s30, 0, 0x10000
	s_cmp_eq_u32 s54, s8
	s_cselect_b32 s9, s1, s9
	s_cselect_b32 s8, s0, s27
	s_cselect_b32 s29, s25, s11
	s_cselect_b32 s28, s24, s10
	s_add_i32 s27, 0, 0x14000
	v_add_u32_e32 v140, s30, v179
	v_add_u32_e32 v156, s27, v179
	ds_read_b128 v[128:131], v140
	ds_read_b128 v[132:135], v140 offset:1024
	ds_read_b128 v[136:139], v140 offset:2048
	ds_read_b128 v[140:143], v140 offset:3072
	ds_read_b128 v[144:147], v156
	ds_read_b128 v[148:151], v156 offset:1024
	ds_read_b128 v[152:155], v156 offset:2048
	ds_read_b128 v[156:159], v156 offset:3072
	v_lshl_add_u64 v[208:209], s[2:3], 0, v[170:171]
	s_add_i32 m0, s47, 0xc000
	ds_read_b128 v[172:175], v228
	ds_read_b128 v[180:183], v228 offset:1024
	ds_read_b128 v[184:187], v228 offset:2048
	ds_read_b128 v[188:191], v228 offset:3072
	ds_read_b128 v[192:195], v228 offset:4096
	ds_read_b128 v[196:199], v228 offset:5120
	ds_read_b128 v[200:203], v228 offset:6144
	ds_read_b128 v[204:207], v228 offset:7168
	global_load_lds_dwordx4 v[208:209], off
	v_lshl_add_u64 v[208:209], s[2:3], 0, v[168:169]
	s_add_i32 m0, s47, 0xe000
	s_nop 0
	global_load_lds_dwordx4 v[208:209], off
	s_waitcnt vmcnt(8)
	s_waitcnt lgkmcnt(0)
	s_barrier
	v_mfma_f32_16x16x32_bf16 v[124:127], v[128:131], v[172:175], v[124:127]
	v_mfma_f32_16x16x32_bf16 v[120:123], v[136:139], v[172:175], v[120:123]
	v_mfma_f32_16x16x32_bf16 v[108:111], v[128:131], v[184:187], v[108:111]
	v_mfma_f32_16x16x32_bf16 v[104:107], v[136:139], v[184:187], v[104:107]
	v_mfma_f32_16x16x32_bf16 v[92:95], v[128:131], v[192:195], v[92:95]
	v_mfma_f32_16x16x32_bf16 v[88:91], v[136:139], v[192:195], v[88:91]
	v_mfma_f32_16x16x32_bf16 v[76:79], v[128:131], v[200:203], v[76:79]
	v_mfma_f32_16x16x32_bf16 v[72:75], v[136:139], v[200:203], v[72:75]
	v_mfma_f32_16x16x32_bf16 v[124:127], v[132:135], v[180:183], v[124:127]
	v_mfma_f32_16x16x32_bf16 v[120:123], v[140:143], v[180:183], v[120:123]
	v_mfma_f32_16x16x32_bf16 v[108:111], v[132:135], v[188:191], v[108:111]
	v_mfma_f32_16x16x32_bf16 v[104:107], v[140:143], v[188:191], v[104:107]
	v_mfma_f32_16x16x32_bf16 v[92:95], v[132:135], v[196:199], v[92:95]
	v_mfma_f32_16x16x32_bf16 v[88:91], v[140:143], v[196:199], v[88:91]
	v_mfma_f32_16x16x32_bf16 v[76:79], v[132:135], v[204:207], v[76:79]
	v_mfma_f32_16x16x32_bf16 v[72:75], v[140:143], v[204:207], v[72:75]
	v_mfma_f32_16x16x32_bf16 v[116:119], v[144:147], v[172:175], v[116:119]
	v_mfma_f32_16x16x32_bf16 v[112:115], v[152:155], v[172:175], v[112:115]
	v_mfma_f32_16x16x32_bf16 v[100:103], v[144:147], v[184:187], v[100:103]
	v_mfma_f32_16x16x32_bf16 v[96:99], v[152:155], v[184:187], v[96:99]
	v_mfma_f32_16x16x32_bf16 v[84:87], v[144:147], v[192:195], v[84:87]
	v_mfma_f32_16x16x32_bf16 v[80:83], v[152:155], v[192:195], v[80:83]
	v_mfma_f32_16x16x32_bf16 v[68:71], v[144:147], v[200:203], v[68:71]
	v_mfma_f32_16x16x32_bf16 v[64:67], v[152:155], v[200:203], v[64:67]
	v_mfma_f32_16x16x32_bf16 v[116:119], v[148:151], v[180:183], v[116:119]
	v_mfma_f32_16x16x32_bf16 v[112:115], v[156:159], v[180:183], v[112:115]
	v_mfma_f32_16x16x32_bf16 v[100:103], v[148:151], v[188:191], v[100:103]
	v_mfma_f32_16x16x32_bf16 v[96:99], v[156:159], v[188:191], v[96:99]
	v_mfma_f32_16x16x32_bf16 v[84:87], v[148:151], v[196:199], v[84:87]
	v_mfma_f32_16x16x32_bf16 v[80:83], v[156:159], v[196:199], v[80:83]
	v_mfma_f32_16x16x32_bf16 v[68:71], v[148:151], v[204:207], v[68:71]
	v_mfma_f32_16x16x32_bf16 v[64:67], v[156:159], v[204:207], v[64:67]
	s_barrier
	s_add_i32 s30, s30, s46
	v_lshl_add_u64 v[208:209], s[28:29], 0, v[162:163]
	s_mov_b32 m0, s30
	ds_read_b128 v[172:175], v228 offset:16384
	ds_read_b128 v[180:183], v228 offset:17408
	ds_read_b128 v[184:187], v228 offset:18432
	ds_read_b128 v[188:191], v228 offset:19456
	ds_read_b128 v[192:195], v228 offset:20480
	ds_read_b128 v[196:199], v228 offset:21504
	ds_read_b128 v[200:203], v228 offset:22528
	ds_read_b128 v[204:207], v228 offset:23552
	global_load_lds_dwordx4 v[208:209], off
	s_add_i32 m0, s30, 0x2000
	v_lshl_add_u64 v[210:211], s[28:29], 0, v[166:167]
	s_add_u32 s28, s28, s88
	s_addc_u32 s29, s29, 0
	s_add_i32 s27, s27, s46
	global_load_lds_dwordx4 v[210:211], off
	v_lshl_add_u64 v[212:213], s[28:29], 0, v[162:163]
	s_mov_b32 m0, s27
	v_lshl_add_u64 v[214:215], s[28:29], 0, v[166:167]
	global_load_lds_dwordx4 v[212:213], off
	s_add_i32 m0, s27, 0x2000
	v_lshl_add_u64 v[230:231], s[8:9], 0, v[160:161]
	global_load_lds_dwordx4 v[214:215], off
	s_mov_b32 m0, s47
	v_lshl_add_u64 v[232:233], s[8:9], 0, v[164:165]
	global_load_lds_dwordx4 v[230:231], off
	s_mov_b32 m0, s48
	s_nop 0
	global_load_lds_dwordx4 v[232:233], off
	s_waitcnt vmcnt(8)
	s_waitcnt lgkmcnt(0)
	s_barrier
; #define PG8_STAGE(bufoff, gbase, voff) do { _Pragma("unroll") for (int _i = 0; _i < 2; ++_i) \
;         __builtin_amdgcn_global_load_lds((const unsigned*)((const char*)(gbase) + (voff)[_i]), (PG8_LAS unsigned*)(lds + (bufoff) + ldsw + _i * 8192), 16, 0, 0); } while (0)
; #define PG8_LDA(dst, b, h) do { _Pragma("unroll") for (int m = 0; m < 4; ++m) _Pragma("unroll") for (int k = 0; k < 2; ++k) dst[m][k] = *(const PG8_LAS bf16x8*)(lds + PG8_SA(b, h) + aoff + m * 2048 + k * 1024); } while (0)
; #define PG8_LDB(dst, b, h) do { _Pragma("unroll") for (int n = 0; n < 2; ++n) _Pragma("unroll") for (int k = 0; k < 2; ++k) dst[n][k] = *(const PG8_LAS bf16x8*)(lds + PG8_SB(b, h) + boff + n * 2048 + k * 1024); } while (0)
; #define PG8_MMA(ai, bj, At, Bt) do { __builtin_amdgcn_s_setprio(1); _Pragma("unroll") for (int m = 0; m < 4; ++m) _Pragma("unroll") for (int n = 0; n < 2; ++n) _Pragma("unroll") for (int k = 0; k < 2; ++k) \
;         acc[ai][bj][m][n] = __builtin_amdgcn_mfma_f32_16x16x32_bf16(Bt[n][k], At[m][k], acc[ai][bj][m][n], 0, 0, 0); __builtin_amdgcn_s_setprio(0); } while (0)
; #define PG8_WAIT_V(n) asm volatile("s_waitcnt vmcnt(" #n ")" ::: "memory")
; template <class Epi, class Sched, bool ALIGN_EPI = false, bool SP2 = false>
; __device__ __forceinline__ void gemm_phase(PG8_LAS unsigned char* lds, const Gemm g, const Sched& S, const Epi& E) {
;     ...
;             PG8_LDB(B0, 0, 0); PG8_LDB(B1, 0, 1); PG8_SCHED; PG8_LDA(At, 0, 0); PG8_STAGE(PG8_SA(1, 1), a1 + hstep, voffA);
;             PG8_WAIT_V(8); PG8_WAIT_L(0); PG8_BAR; PG8_MMA(0, 0, At, B0); PG8_MMA(0, 1, At, B1); PG8_BAR; PG8_SCHED;
;             PG8_LDA(At, 0, 1); PG8_STAGE(PG8_SB(0, 0), b2, voffB); PG8_STAGE(PG8_SB(0, 1), b2 + hstep, voffB); PG8_STAGE(PG8_SA(0, 0), a2, voffA);
;             PG8_WAIT_V(8); PG8_WAIT_L(0); PG8_BAR; PG8_MMA(1, 0, At, B0); PG8_MMA(1, 1, At, B1); PG8_BAR; PG8_SCHED;
;             PG8_LDB(B0, 1, 0); PG8_LDB(B1, 1, 1); PG8_SCHED; PG8_LDA(At, 1, 0); PG8_STAGE(PG8_SA(0, 1), a2 + hstep, voffA);
;             PG8_WAIT_V(8); PG8_WAIT_L(0); PG8_BAR; PG8_MMA(0, 0, At, B0); PG8_MMA(0, 1, At, B1); PG8_BAR; PG8_SCHED;
;             PG8_LDA(At, 1, 1); PG8_STAGE(PG8_SB(1, 0), b3, voffB); PG8_STAGE(PG8_SB(1, 1), b3 + hstep, voffB); PG8_STAGE(PG8_SA(1, 0), a3, voffA);
;             PG8_WAIT_V(8); PG8_WAIT_L(0); PG8_BAR; PG8_MMA(1, 0, At, B0); PG8_MMA(1, 1, At, B1); PG8_BAR; PG8_SCHED;
	v_mfma_f32_16x16x32_bf16 v[60:63], v[128:131], v[172:175], v[60:63]
	v_mfma_f32_16x16x32_bf16 v[56:59], v[136:139], v[172:175], v[56:59]
	v_mfma_f32_16x16x32_bf16 v[44:47], v[128:131], v[184:187], v[44:47]
	v_mfma_f32_16x16x32_bf16 v[40:43], v[136:139], v[184:187], v[40:43]
	v_mfma_f32_16x16x32_bf16 v[28:31], v[128:131], v[192:195], v[28:31]
	v_mfma_f32_16x16x32_bf16 v[24:27], v[136:139], v[192:195], v[24:27]
	v_mfma_f32_16x16x32_bf16 v[12:15], v[128:131], v[200:203], v[12:15]
	v_mfma_f32_16x16x32_bf16 v[8:11], v[136:139], v[200:203], v[8:11]
	v_mfma_f32_16x16x32_bf16 v[60:63], v[132:135], v[180:183], v[60:63]
	v_mfma_f32_16x16x32_bf16 v[56:59], v[140:143], v[180:183], v[56:59]
	v_mfma_f32_16x16x32_bf16 v[44:47], v[132:135], v[188:191], v[44:47]
	v_mfma_f32_16x16x32_bf16 v[40:43], v[140:143], v[188:191], v[40:43]
	v_mfma_f32_16x16x32_bf16 v[28:31], v[132:135], v[196:199], v[28:31]
	v_mfma_f32_16x16x32_bf16 v[24:27], v[140:143], v[196:199], v[24:27]
	v_mfma_f32_16x16x32_bf16 v[12:15], v[132:135], v[204:207], v[12:15]
	v_mfma_f32_16x16x32_bf16 v[8:11], v[140:143], v[204:207], v[8:11]
	v_mfma_f32_16x16x32_bf16 v[52:55], v[144:147], v[172:175], v[52:55]
	v_mfma_f32_16x16x32_bf16 v[48:51], v[152:155], v[172:175], v[48:51]
	v_mfma_f32_16x16x32_bf16 v[36:39], v[144:147], v[184:187], v[36:39]
	v_mfma_f32_16x16x32_bf16 v[32:35], v[152:155], v[184:187], v[32:35]
	v_mfma_f32_16x16x32_bf16 v[20:23], v[144:147], v[192:195], v[20:23]
	v_mfma_f32_16x16x32_bf16 v[16:19], v[152:155], v[192:195], v[16:19]
	v_mfma_f32_16x16x32_bf16 v[4:7], v[144:147], v[200:203], v[4:7]
	v_mfma_f32_16x16x32_bf16 v[0:3], v[152:155], v[200:203], v[0:3]
	v_mfma_f32_16x16x32_bf16 v[52:55], v[148:151], v[180:183], v[52:55]
	v_mfma_f32_16x16x32_bf16 v[48:51], v[156:159], v[180:183], v[48:51]
	v_mfma_f32_16x16x32_bf16 v[36:39], v[148:151], v[188:191], v[36:39]
	v_mfma_f32_16x16x32_bf16 v[32:35], v[156:159], v[188:191], v[32:35]
	v_mfma_f32_16x16x32_bf16 v[20:23], v[148:151], v[196:199], v[20:23]
	v_mfma_f32_16x16x32_bf16 v[16:19], v[156:159], v[196:199], v[16:19]
	v_mfma_f32_16x16x32_bf16 v[4:7], v[148:151], v[204:207], v[4:7]
	v_mfma_f32_16x16x32_bf16 v[0:3], v[156:159], v[204:207], v[0:3]
	s_barrier
	s_add_i32 s27, 0, 0x18000
	s_add_i32 s28, 0, 0x1c000
	v_add_u32_e32 v140, s27, v179
	v_add_u32_e32 v156, s28, v179
	ds_read_b128 v[128:131], v140
	ds_read_b128 v[132:135], v140 offset:1024
	ds_read_b128 v[136:139], v140 offset:2048
	ds_read_b128 v[140:143], v140 offset:3072
	ds_read_b128 v[144:147], v156
	ds_read_b128 v[148:151], v156 offset:1024
	ds_read_b128 v[152:155], v156 offset:2048
	ds_read_b128 v[156:159], v156 offset:3072
	s_add_u32 s8, s8, s88
	s_addc_u32 s9, s9, 0
	s_mov_b32 m0, s49
	v_lshl_add_u64 v[234:235], s[8:9], 0, v[160:161]
	ds_read_b128 v[172:175], v228 offset:32768
	ds_read_b128 v[180:183], v228 offset:33792
	ds_read_b128 v[184:187], v228 offset:34816
	ds_read_b128 v[188:191], v228 offset:35840
	ds_read_b128 v[192:195], v228 offset:36864
	ds_read_b128 v[196:199], v228 offset:37888
	ds_read_b128 v[200:203], v228 offset:38912
	ds_read_b128 v[204:207], v228 offset:39936
	global_load_lds_dwordx4 v[234:235], off
	v_lshl_add_u64 v[234:235], s[8:9], 0, v[164:165]
	s_mov_b32 m0, s50
	s_nop 0
	global_load_lds_dwordx4 v[234:235], off
	s_waitcnt vmcnt(8)
	s_waitcnt lgkmcnt(0)
	s_barrier
	v_mfma_f32_16x16x32_bf16 v[124:127], v[128:131], v[172:175], v[124:127]
	v_mfma_f32_16x16x32_bf16 v[120:123], v[136:139], v[172:175], v[120:123]
	v_mfma_f32_16x16x32_bf16 v[108:111], v[128:131], v[184:187], v[108:111]
	v_mfma_f32_16x16x32_bf16 v[104:107], v[136:139], v[184:187], v[104:107]
	v_mfma_f32_16x16x32_bf16 v[92:95], v[128:131], v[192:195], v[92:95]
	v_mfma_f32_16x16x32_bf16 v[88:91], v[136:139], v[192:195], v[88:91]
	v_mfma_f32_16x16x32_bf16 v[76:79], v[128:131], v[200:203], v[76:79]
	v_mfma_f32_16x16x32_bf16 v[72:75], v[136:139], v[200:203], v[72:75]
	v_mfma_f32_16x16x32_bf16 v[124:127], v[132:135], v[180:183], v[124:127]
	v_mfma_f32_16x16x32_bf16 v[120:123], v[140:143], v[180:183], v[120:123]
	v_mfma_f32_16x16x32_bf16 v[108:111], v[132:135], v[188:191], v[108:111]
	v_mfma_f32_16x16x32_bf16 v[104:107], v[140:143], v[188:191], v[104:107]
	v_mfma_f32_16x16x32_bf16 v[92:95], v[132:135], v[196:199], v[92:95]
	v_mfma_f32_16x16x32_bf16 v[88:91], v[140:143], v[196:199], v[88:91]
	v_mfma_f32_16x16x32_bf16 v[76:79], v[132:135], v[204:207], v[76:79]
	v_mfma_f32_16x16x32_bf16 v[72:75], v[140:143], v[204:207], v[72:75]
	v_mfma_f32_16x16x32_bf16 v[116:119], v[144:147], v[172:175], v[116:119]
	v_mfma_f32_16x16x32_bf16 v[112:115], v[152:155], v[172:175], v[112:115]
	v_mfma_f32_16x16x32_bf16 v[100:103], v[144:147], v[184:187], v[100:103]
	v_mfma_f32_16x16x32_bf16 v[96:99], v[152:155], v[184:187], v[96:99]
	v_mfma_f32_16x16x32_bf16 v[84:87], v[144:147], v[192:195], v[84:87]
	v_mfma_f32_16x16x32_bf16 v[80:83], v[152:155], v[192:195], v[80:83]
	v_mfma_f32_16x16x32_bf16 v[68:71], v[144:147], v[200:203], v[68:71]
	v_mfma_f32_16x16x32_bf16 v[64:67], v[152:155], v[200:203], v[64:67]
	v_mfma_f32_16x16x32_bf16 v[116:119], v[148:151], v[180:183], v[116:119]
	v_mfma_f32_16x16x32_bf16 v[112:115], v[156:159], v[180:183], v[112:115]
	v_mfma_f32_16x16x32_bf16 v[100:103], v[148:151], v[188:191], v[100:103]
	v_mfma_f32_16x16x32_bf16 v[96:99], v[156:159], v[188:191], v[96:99]
	v_mfma_f32_16x16x32_bf16 v[84:87], v[148:151], v[196:199], v[84:87]
	v_mfma_f32_16x16x32_bf16 v[80:83], v[156:159], v[196:199], v[80:83]
	v_mfma_f32_16x16x32_bf16 v[68:71], v[148:151], v[204:207], v[68:71]
	v_mfma_f32_16x16x32_bf16 v[64:67], v[156:159], v[204:207], v[64:67]
	s_barrier
; #define PG8_STAGE(bufoff, gbase, voff) do { _Pragma("unroll") for (int _i = 0; _i < 2; ++_i) \
;         __builtin_amdgcn_global_load_lds((const unsigned*)((const char*)(gbase) + (voff)[_i]), (PG8_LAS unsigned*)(lds + (bufoff) + ldsw + _i * 8192), 16, 0, 0); } while (0)
; #define PG8_LDA(dst, b, h) do { _Pragma("unroll") for (int m = 0; m < 4; ++m) _Pragma("unroll") for (int k = 0; k < 2; ++k) dst[m][k] = *(const PG8_LAS bf16x8*)(lds + PG8_SA(b, h) + aoff + m * 2048 + k * 1024); } while (0)
; #define PG8_LDB(dst, b, h) do { _Pragma("unroll") for (int n = 0; n < 2; ++n) _Pragma("unroll") for (int k = 0; k < 2; ++k) dst[n][k] = *(const PG8_LAS bf16x8*)(lds + PG8_SB(b, h) + boff + n * 2048 + k * 1024); } while (0)
; template <class Epi, class Sched, bool ALIGN_EPI = false, bool SP2 = false>
; __device__ __forceinline__ void gemm_phase(PG8_LAS unsigned char* lds, const Gemm g, const Sched& S, const Epi& E) {
;     ...
;         for (int t = 0; t < nt; t += 2) {
;             const bool last = (t == nt - 2);
;             const char* a1 = cA + (size_t)(t + 1) * kstep;
;             const char* a2 = last ? nA : cA + (size_t)(t + 2) * kstep; const char* b2 = last ? nB : cB + (size_t)(t + 2) * kstep;
;             const char* a3 = a2 + kstep; const char* b3 = b2 + kstep;
;             if (last && has_next) S.a_ready(nxt);
;             if constexpr (SP2) {
;             PG8_LDB(B0, 0, 0); PG8_LDB(B1, 0, 1); PG8_SCHED; PG8_LDA(At, 0, 0); PG8_STAGE(PG8_SA(1, 1), a1 + hstep, voffA);
;             PG8_WAIT_V(8); PG8_WAIT_L(0); PG8_BAR; PG8_MMA(0, 0, At, B0); PG8_MMA(0, 1, At, B1); PG8_BAR; PG8_SCHED;
;             PG8_LDA(At, 0, 1); PG8_STAGE(PG8_SB(0, 0), b2, voffB); PG8_STAGE(PG8_SB(0, 1), b2 + hstep, voffB); PG8_STAGE(PG8_SA(0, 0), a2, voffA);
;             PG8_WAIT_V(8); PG8_WAIT_L(0); PG8_BAR; PG8_MMA(1, 0, At, B0); PG8_MMA(1, 1, At, B1); PG8_BAR; PG8_SCHED;
;             PG8_LDB(B0, 1, 0); PG8_LDB(B1, 1, 1); PG8_SCHED; PG8_LDA(At, 1, 0); PG8_STAGE(PG8_SA(0, 1), a2 + hstep, voffA);
;             PG8_WAIT_V(8); PG8_WAIT_L(0); PG8_BAR; PG8_MMA(0, 0, At, B0); PG8_MMA(0, 1, At, B1); PG8_BAR; PG8_SCHED;
;             PG8_LDA(At, 1, 1); PG8_STAGE(PG8_SB(1, 0), b3, voffB); PG8_STAGE(PG8_SB(1, 1), b3 + hstep, voffB); PG8_STAGE(PG8_SA(1, 0), a3, voffA);
;             PG8_WAIT_V(8); PG8_WAIT_L(0); PG8_BAR; PG8_MMA(1, 0, At, B0); PG8_MMA(1, 1, At, B1); PG8_BAR; PG8_SCHED;
	s_add_i32 s8, s27, s46
	v_lshl_add_u64 v[208:209], v[208:209], 0, s[94:95]
	s_mov_b32 m0, s8
	ds_read_b128 v[172:175], v228 offset:49152
	ds_read_b128 v[180:183], v228 offset:50176
	ds_read_b128 v[184:187], v228 offset:51200
	ds_read_b128 v[188:191], v228 offset:52224
	ds_read_b128 v[192:195], v228 offset:53248
	ds_read_b128 v[196:199], v228 offset:54272
	ds_read_b128 v[200:203], v228 offset:55296
	ds_read_b128 v[204:207], v228 offset:56320
	global_load_lds_dwordx4 v[208:209], off
	v_lshl_add_u64 v[208:209], v[210:211], 0, s[94:95]
	s_add_i32 m0, s8, 0x2000
	s_add_i32 s8, s28, s46
	global_load_lds_dwordx4 v[208:209], off
	v_lshl_add_u64 v[208:209], v[212:213], 0, s[94:95]
	s_mov_b32 m0, s8
	s_nop 0
	global_load_lds_dwordx4 v[208:209], off
	v_lshl_add_u64 v[208:209], v[214:215], 0, s[94:95]
	s_add_i32 m0, s8, 0x2000
	s_nop 0
	global_load_lds_dwordx4 v[208:209], off
	v_lshl_add_u64 v[208:209], v[230:231], 0, s[94:95]
	s_mov_b32 m0, s52
	s_nop 0
	global_load_lds_dwordx4 v[208:209], off
	v_lshl_add_u64 v[208:209], v[232:233], 0, s[94:95]
	s_mov_b32 m0, s53
	s_nop 0
	global_load_lds_dwordx4 v[208:209], off
	s_waitcnt vmcnt(8)
	s_waitcnt lgkmcnt(0)
	s_barrier
	v_mfma_f32_16x16x32_bf16 v[60:63], v[128:131], v[172:175], v[60:63]
	v_mfma_f32_16x16x32_bf16 v[56:59], v[136:139], v[172:175], v[56:59]
	v_mfma_f32_16x16x32_bf16 v[44:47], v[128:131], v[184:187], v[44:47]
	v_mfma_f32_16x16x32_bf16 v[40:43], v[136:139], v[184:187], v[40:43]
	v_mfma_f32_16x16x32_bf16 v[28:31], v[128:131], v[192:195], v[28:31]
	v_mfma_f32_16x16x32_bf16 v[24:27], v[136:139], v[192:195], v[24:27]
	v_mfma_f32_16x16x32_bf16 v[12:15], v[128:131], v[200:203], v[12:15]
	v_mfma_f32_16x16x32_bf16 v[8:11], v[136:139], v[200:203], v[8:11]
	v_mfma_f32_16x16x32_bf16 v[60:63], v[132:135], v[180:183], v[60:63]
	v_mfma_f32_16x16x32_bf16 v[56:59], v[140:143], v[180:183], v[56:59]
	v_mfma_f32_16x16x32_bf16 v[44:47], v[132:135], v[188:191], v[44:47]
	v_mfma_f32_16x16x32_bf16 v[40:43], v[140:143], v[188:191], v[40:43]
	v_mfma_f32_16x16x32_bf16 v[28:31], v[132:135], v[196:199], v[28:31]
	v_mfma_f32_16x16x32_bf16 v[24:27], v[140:143], v[196:199], v[24:27]
	v_mfma_f32_16x16x32_bf16 v[12:15], v[132:135], v[204:207], v[12:15]
	v_mfma_f32_16x16x32_bf16 v[8:11], v[140:143], v[204:207], v[8:11]
	v_mfma_f32_16x16x32_bf16 v[52:55], v[144:147], v[172:175], v[52:55]
	v_mfma_f32_16x16x32_bf16 v[48:51], v[152:155], v[172:175], v[48:51]
	v_mfma_f32_16x16x32_bf16 v[36:39], v[144:147], v[184:187], v[36:39]
	v_mfma_f32_16x16x32_bf16 v[32:35], v[152:155], v[184:187], v[32:35]
	v_mfma_f32_16x16x32_bf16 v[20:23], v[144:147], v[192:195], v[20:23]
	v_mfma_f32_16x16x32_bf16 v[16:19], v[152:155], v[192:195], v[16:19]
	v_mfma_f32_16x16x32_bf16 v[4:7], v[144:147], v[200:203], v[4:7]
	v_mfma_f32_16x16x32_bf16 v[0:3], v[152:155], v[200:203], v[0:3]
	v_mfma_f32_16x16x32_bf16 v[52:55], v[148:151], v[180:183], v[52:55]
	v_mfma_f32_16x16x32_bf16 v[48:51], v[156:159], v[180:183], v[48:51]
	v_mfma_f32_16x16x32_bf16 v[36:39], v[148:151], v[188:191], v[36:39]
	v_mfma_f32_16x16x32_bf16 v[32:35], v[156:159], v[188:191], v[32:35]
	v_mfma_f32_16x16x32_bf16 v[20:23], v[148:151], v[196:199], v[20:23]
	v_mfma_f32_16x16x32_bf16 v[16:19], v[156:159], v[196:199], v[16:19]
	v_mfma_f32_16x16x32_bf16 v[4:7], v[148:151], v[204:207], v[4:7]
	v_mfma_f32_16x16x32_bf16 v[0:3], v[156:159], v[204:207], v[0:3]
	s_barrier
	s_add_u32 s10, s10, 0x100
	s_addc_u32 s11, s11, 0
	s_add_u32 s2, s2, 0x100
	s_addc_u32 s3, s3, 0
	s_cmp_ge_u32 s26, s51
	s_mov_b32 s8, s26
	s_cbranch_scc0 .LBB0_307
	s_and_b64 vcc, exec, s[22:23]
	s_cbranch_vccz .LBB0_310
	s_barrier
